# P1 small-gemm q/k-norm epilogue: row-invariant norm-gain loads hoisted (loaded once), 15 reload+wait pairs removed
# baseline (speedup 1.0000x reference)
; __device__ __forceinline__ unsigned f2bf(float f) { unsigned u = __builtin_bit_cast(unsigned, f); return (u + 0x7fffu + ((u >> 16) & 1u)) >> 16; }
;     __device__ __forceinline__ void operator()(const f32x16& acc0, const f32x16& acc1, int rb, int cg, int r32, int hi, const float (&ss)[16]) const {
;     ...
;             } else if (pn < 10) {
;                 float q = v0 * v0 + v1 * v1;
;                 q += __shfl_xor(q, 1); q += __shfl_xor(q, 2); q += __shfl_xor(q, 4); q += __shfl_xor(q, 8); q += __shfl_xor(q, 16);
;                 const float rn = rsqrtf(q * (1.0f / 64.0f) + EPS);
;                 const bool isq = pn < 8;
;                 const float* gp = isq ? qg : kg;
;                 const int col = ((pn & 1) * 4 + hd) * 64 + r32;
;                 const float a0 = v0 * rn * gp[r32], a1 = v1 * rn * gp[32 + r32];
;                 if (isq) { bf16_t* SQ = (bf16_t*)(ws + WS_SQ); SQ[(size_t)row * 512 + col] = (bf16_t)f2bf(a0 * QSCALE); SQ[(size_t)row * 512 + col + 32] = (bf16_t)f2bf(a1 * QSCALE); }
;                 else { bf16_t* KB = (bf16_t*)(ws + WS_KB); KB[(size_t)row * 512 + col] = (bf16_t)f2bf(a0); KB[(size_t)row * 512 + col + 32] = (bf16_t)f2bf(a1);
;                     Ks[(size_t)rs_ * 512 + col] = a0; Ks[(size_t)rs_ * 512 + col + 32] = a1; }
.LBB0_284:
	s_andn2_b64 vcc, exec, s[10:11]
	s_cbranch_vccnz .LBB0_289
	s_and_b64 s[10:11], s[44:45], exec
	s_cselect_b32 s11, s62, s64
	s_cselect_b32 s10, s61, s63
	v_lshlrev_b32_e32 v0, 2, v98
	global_load_dword v198, v0, s[10:11]
	s_nop 0
	global_load_dword v199, v0, s[10:11] offset:128
	v_pk_mul_f32 v[66:67], v[62:63], v[62:63]
	s_and_b64 s[10:11], exec, s[42:43]
	v_add_f32_e32 v61, v66, v67
	ds_bpermute_b32 v66, v69, v61
	v_xor_b32_e32 v67, 16, v205
	v_cmp_lt_i32_e32 vcc, v67, v68
	s_mov_b64 s[46:47], -1
	s_waitcnt lgkmcnt(0)
	v_add_f32_e32 v61, v61, v66
	ds_bpermute_b32 v66, v70, v61
	v_cndmask_b32_e32 v67, v205, v67, vcc
	v_lshlrev_b32_e32 v67, 2, v67
	s_waitcnt lgkmcnt(0)
	v_add_f32_e32 v61, v61, v66
	ds_bpermute_b32 v66, v71, v61
	s_waitcnt lgkmcnt(0)
	v_add_f32_e32 v61, v61, v66
	ds_bpermute_b32 v66, v72, v61
	s_waitcnt lgkmcnt(0)
	v_add_f32_e32 v61, v61, v66
	ds_bpermute_b32 v66, v67, v61
	s_waitcnt lgkmcnt(0)
	v_add_f32_e32 v61, v61, v66
	v_fmamk_f32 v61, v61, 0x3c800000, v201
	v_mul_f32_e32 v66, 0x4b800000, v61
	v_cmp_gt_f32_e32 vcc, s3, v61
	s_nop 1
	v_cndmask_b32_e32 v61, v61, v66, vcc
	v_rsq_f32_e32 v61, v61
	s_nop 0
	v_mul_f32_e32 v66, 0x45800000, v61
	v_cndmask_b32_e32 v61, v61, v66, vcc
	v_mul_f32_e32 v66, v62, v61
	v_mul_f32_e32 v61, v63, v61
	s_mov_b64 vcc, s[10:11]
	s_waitcnt vmcnt(1)
	v_mul_f32_e32 v51, v198, v66
	s_waitcnt vmcnt(0)
	v_mul_f32_e32 v0, v199, v61
	s_cbranch_vccz .LBB0_287
	v_bfe_u32 v61, v51, 16, 1
	v_lshlrev_b64 v[66:67], 10, v[64:65]
	v_add3_u32 v61, v51, v61, s2
	v_lshl_add_u64 v[66:67], v[54:55], 0, v[66:67]
	global_store_short_d16_hi v[66:67], v61, off
	v_bfe_u32 v61, v0, 16, 1
	v_add3_u32 v61, v0, v61, s2
	global_store_short_d16_hi v[66:67], v61, off offset:64
	v_ashrrev_i32_e32 v61, 31, v60
	v_lshlrev_b64 v[66:67], 11, v[60:61]
	v_lshl_add_u64 v[66:67], v[52:53], 0, v[66:67]
	global_store_dword v[66:67], v51, off
	global_store_dword v[66:67], v0, off offset:128
	s_mov_b64 s[46:47], 0

; __device__ __forceinline__ unsigned f2bf(float f) { unsigned u = __builtin_bit_cast(unsigned, f); return (u + 0x7fffu + ((u >> 16) & 1u)) >> 16; }
;     __device__ __forceinline__ void operator()(const f32x16& acc0, const f32x16& acc1, int rb, int cg, int r32, int hi, const float (&ss)[16]) const {
;     ...
;             } else if (pn < 10) {
;                 float q = v0 * v0 + v1 * v1;
;                 q += __shfl_xor(q, 1); q += __shfl_xor(q, 2); q += __shfl_xor(q, 4); q += __shfl_xor(q, 8); q += __shfl_xor(q, 16);
;                 const float rn = rsqrtf(q * (1.0f / 64.0f) + EPS);
;                 const bool isq = pn < 8;
;                 const float* gp = isq ? qg : kg;
;                 const int col = ((pn & 1) * 4 + hd) * 64 + r32;
;                 const float a0 = v0 * rn * gp[r32], a1 = v1 * rn * gp[32 + r32];
;                 if (isq) { bf16_t* SQ = (bf16_t*)(ws + WS_SQ); SQ[(size_t)row * 512 + col] = (bf16_t)f2bf(a0 * QSCALE); SQ[(size_t)row * 512 + col + 32] = (bf16_t)f2bf(a1 * QSCALE); }
;                 else { bf16_t* KB = (bf16_t*)(ws + WS_KB); KB[(size_t)row * 512 + col] = (bf16_t)f2bf(a0); KB[(size_t)row * 512 + col + 32] = (bf16_t)f2bf(a1);
;                     Ks[(size_t)rs_ * 512 + col] = a0; Ks[(size_t)rs_ * 512 + col + 32] = a1; }
.LBB0_300:
	s_andn2_b64 vcc, exec, s[16:17]
	s_cbranch_vccnz .LBB0_305
	s_and_b64 s[16:17], s[44:45], exec
	s_cselect_b32 s17, s62, s64
	s_cselect_b32 s16, s61, s63
	v_lshlrev_b32_e32 v0, 2, v98
	s_nop 0
	v_pk_mul_f32 v[74:75], v[62:63], v[62:63]
	v_xor_b32_e32 v67, 16, v205
	v_add_f32_e32 v51, v74, v75
	ds_bpermute_b32 v61, v69, v51
	v_cmp_lt_i32_e32 vcc, v67, v68
	s_waitcnt lgkmcnt(0)
	v_add_f32_e32 v51, v51, v61
	ds_bpermute_b32 v61, v70, v51
	v_cndmask_b32_e32 v67, v205, v67, vcc
	v_lshlrev_b32_e32 v67, 2, v67
	s_andn2_b64 vcc, exec, s[42:43]
	s_waitcnt lgkmcnt(0)
	v_add_f32_e32 v51, v51, v61
	ds_bpermute_b32 v61, v71, v51
	s_waitcnt lgkmcnt(0)
	v_add_f32_e32 v51, v51, v61
	ds_bpermute_b32 v61, v72, v51
	s_waitcnt lgkmcnt(0)
	v_add_f32_e32 v51, v51, v61
	ds_bpermute_b32 v61, v67, v51
	s_waitcnt lgkmcnt(0)
	v_add_f32_e32 v51, v51, v61
	v_fmamk_f32 v51, v51, 0x3c800000, v201
	v_mul_f32_e32 v61, 0x4b800000, v51
	v_cmp_gt_f32_e64 s[16:17], s3, v51
	s_nop 1
	v_cndmask_b32_e64 v51, v51, v61, s[16:17]
	v_rsq_f32_e32 v51, v51
	s_nop 0
	v_mul_f32_e32 v61, 0x45800000, v51
	v_cndmask_b32_e64 v51, v51, v61, s[16:17]
	v_mul_f32_e32 v61, v62, v51
	v_mul_f32_e32 v51, v63, v51
	s_mov_b64 s[16:17], -1
	v_mul_f32_e32 v41, v198, v61
	v_mul_f32_e32 v0, v199, v51
	s_cbranch_vccnz .LBB0_303
	v_bfe_u32 v51, v41, 16, 1
	v_lshlrev_b64 v[74:75], 10, v[64:65]
	v_add3_u32 v51, v41, v51, s2
	v_lshl_add_u64 v[74:75], v[54:55], 0, v[74:75]
	v_ashrrev_i32_e32 v67, 31, v66
	global_store_short_d16_hi v[74:75], v51, off
	v_bfe_u32 v51, v0, 16, 1
	v_lshlrev_b64 v[66:67], 11, v[66:67]
	v_add3_u32 v51, v0, v51, s2
	v_lshl_add_u64 v[66:67], v[52:53], 0, v[66:67]
	s_mov_b64 s[16:17], 0
	global_store_short_d16_hi v[74:75], v51, off offset:64
	global_store_dword v[66:67], v41, off
	global_store_dword v[66:67], v0, off offset:128

; __device__ __forceinline__ unsigned f2bf(float f) { unsigned u = __builtin_bit_cast(unsigned, f); return (u + 0x7fffu + ((u >> 16) & 1u)) >> 16; }
;     __device__ __forceinline__ void operator()(const f32x16& acc0, const f32x16& acc1, int rb, int cg, int r32, int hi, const float (&ss)[16]) const {
;     ...
;             } else if (pn < 10) {
;                 float q = v0 * v0 + v1 * v1;
;                 q += __shfl_xor(q, 1); q += __shfl_xor(q, 2); q += __shfl_xor(q, 4); q += __shfl_xor(q, 8); q += __shfl_xor(q, 16);
;                 const float rn = rsqrtf(q * (1.0f / 64.0f) + EPS);
;                 const bool isq = pn < 8;
;                 const float* gp = isq ? qg : kg;
;                 const int col = ((pn & 1) * 4 + hd) * 64 + r32;
;                 const float a0 = v0 * rn * gp[r32], a1 = v1 * rn * gp[32 + r32];
;                 if (isq) { bf16_t* SQ = (bf16_t*)(ws + WS_SQ); SQ[(size_t)row * 512 + col] = (bf16_t)f2bf(a0 * QSCALE); SQ[(size_t)row * 512 + col + 32] = (bf16_t)f2bf(a1 * QSCALE); }
;                 else { bf16_t* KB = (bf16_t*)(ws + WS_KB); KB[(size_t)row * 512 + col] = (bf16_t)f2bf(a0); KB[(size_t)row * 512 + col + 32] = (bf16_t)f2bf(a1);
;                     Ks[(size_t)rs_ * 512 + col] = a0; Ks[(size_t)rs_ * 512 + col + 32] = a1; }
.LBB0_316:
	s_andn2_b64 vcc, exec, s[16:17]
	s_cbranch_vccnz .LBB0_321
	s_and_b64 s[16:17], s[44:45], exec
	s_cselect_b32 s17, s62, s64
	s_cselect_b32 s16, s61, s63
	v_lshlrev_b32_e32 v0, 2, v98
	s_nop 0
	v_pk_mul_f32 v[74:75], v[62:63], v[62:63]
	v_xor_b32_e32 v61, 16, v205
	v_add_f32_e32 v47, v74, v75
	ds_bpermute_b32 v51, v69, v47
	v_cmp_lt_i32_e32 vcc, v61, v68
	s_waitcnt lgkmcnt(0)
	v_add_f32_e32 v47, v47, v51
	ds_bpermute_b32 v51, v70, v47
	v_cndmask_b32_e32 v61, v205, v61, vcc
	v_lshlrev_b32_e32 v61, 2, v61
	s_andn2_b64 vcc, exec, s[42:43]
	s_waitcnt lgkmcnt(0)
	v_add_f32_e32 v47, v47, v51
	ds_bpermute_b32 v51, v71, v47
	s_waitcnt lgkmcnt(0)
	v_add_f32_e32 v47, v47, v51
	ds_bpermute_b32 v51, v72, v47
	s_waitcnt lgkmcnt(0)
	v_add_f32_e32 v47, v47, v51
	ds_bpermute_b32 v51, v61, v47
	s_waitcnt lgkmcnt(0)
	v_add_f32_e32 v47, v47, v51
	v_fmamk_f32 v47, v47, 0x3c800000, v201
	v_mul_f32_e32 v51, 0x4b800000, v47
	v_cmp_gt_f32_e64 s[16:17], s3, v47
	s_nop 1
	v_cndmask_b32_e64 v47, v47, v51, s[16:17]
	v_rsq_f32_e32 v47, v47
	s_nop 0
	v_mul_f32_e32 v51, 0x45800000, v47
	v_cndmask_b32_e64 v47, v47, v51, s[16:17]
	v_mul_f32_e32 v51, v62, v47
	v_mul_f32_e32 v47, v63, v47
	s_mov_b64 s[16:17], -1
	v_mul_f32_e32 v41, v198, v51
	v_mul_f32_e32 v0, v199, v47
	s_cbranch_vccnz .LBB0_319
	v_bfe_u32 v47, v41, 16, 1
	v_lshlrev_b64 v[74:75], 10, v[64:65]
	v_add3_u32 v47, v41, v47, s2
	v_lshl_add_u64 v[74:75], v[54:55], 0, v[74:75]
	v_ashrrev_i32_e32 v67, 31, v66
	global_store_short_d16_hi v[74:75], v47, off
	v_bfe_u32 v47, v0, 16, 1
	v_lshlrev_b64 v[66:67], 11, v[66:67]
	v_add3_u32 v47, v0, v47, s2
	v_lshl_add_u64 v[66:67], v[52:53], 0, v[66:67]
	s_mov_b64 s[16:17], 0
	global_store_short_d16_hi v[74:75], v47, off offset:64
	global_store_dword v[66:67], v41, off
	global_store_dword v[66:67], v0, off offset:128

; __device__ __forceinline__ unsigned f2bf(float f) { unsigned u = __builtin_bit_cast(unsigned, f); return (u + 0x7fffu + ((u >> 16) & 1u)) >> 16; }
;     __device__ __forceinline__ void operator()(const f32x16& acc0, const f32x16& acc1, int rb, int cg, int r32, int hi, const float (&ss)[16]) const {
;     ...
;             } else if (pn < 10) {
;                 float q = v0 * v0 + v1 * v1;
;                 q += __shfl_xor(q, 1); q += __shfl_xor(q, 2); q += __shfl_xor(q, 4); q += __shfl_xor(q, 8); q += __shfl_xor(q, 16);
;                 const float rn = rsqrtf(q * (1.0f / 64.0f) + EPS);
;                 const bool isq = pn < 8;
;                 const float* gp = isq ? qg : kg;
;                 const int col = ((pn & 1) * 4 + hd) * 64 + r32;
;                 const float a0 = v0 * rn * gp[r32], a1 = v1 * rn * gp[32 + r32];
;                 if (isq) { bf16_t* SQ = (bf16_t*)(ws + WS_SQ); SQ[(size_t)row * 512 + col] = (bf16_t)f2bf(a0 * QSCALE); SQ[(size_t)row * 512 + col + 32] = (bf16_t)f2bf(a1 * QSCALE); }
;                 else { bf16_t* KB = (bf16_t*)(ws + WS_KB); KB[(size_t)row * 512 + col] = (bf16_t)f2bf(a0); KB[(size_t)row * 512 + col + 32] = (bf16_t)f2bf(a1);
;                     Ks[(size_t)rs_ * 512 + col] = a0; Ks[(size_t)rs_ * 512 + col + 32] = a1; }
.LBB0_332:
	s_andn2_b64 vcc, exec, s[16:17]
	s_cbranch_vccnz .LBB0_337
	s_and_b64 s[16:17], s[44:45], exec
	s_cselect_b32 s17, s62, s64
	s_cselect_b32 s16, s61, s63
	v_lshlrev_b32_e32 v0, 2, v98
	s_nop 0
	v_pk_mul_f32 v[74:75], v[62:63], v[62:63]
	v_xor_b32_e32 v51, 16, v205
	v_add_f32_e32 v41, v74, v75
	ds_bpermute_b32 v47, v69, v41
	v_cmp_lt_i32_e32 vcc, v51, v68
	s_waitcnt lgkmcnt(0)
	v_add_f32_e32 v41, v41, v47
	ds_bpermute_b32 v47, v70, v41
	v_cndmask_b32_e32 v51, v205, v51, vcc
	v_lshlrev_b32_e32 v51, 2, v51
	s_andn2_b64 vcc, exec, s[42:43]
	s_waitcnt lgkmcnt(0)
	v_add_f32_e32 v41, v41, v47
	ds_bpermute_b32 v47, v71, v41
	s_waitcnt lgkmcnt(0)
	v_add_f32_e32 v41, v41, v47
	ds_bpermute_b32 v47, v72, v41
	s_waitcnt lgkmcnt(0)
	v_add_f32_e32 v41, v41, v47
	ds_bpermute_b32 v47, v51, v41
	s_waitcnt lgkmcnt(0)
	v_add_f32_e32 v41, v41, v47
	v_fmamk_f32 v41, v41, 0x3c800000, v201
	v_mul_f32_e32 v47, 0x4b800000, v41
	v_cmp_gt_f32_e64 s[16:17], s3, v41
	s_nop 1
	v_cndmask_b32_e64 v41, v41, v47, s[16:17]
	v_rsq_f32_e32 v41, v41
	s_nop 0
	v_mul_f32_e32 v47, 0x45800000, v41
	v_cndmask_b32_e64 v41, v41, v47, s[16:17]
	v_mul_f32_e32 v47, v62, v41
	v_mul_f32_e32 v41, v63, v41
	s_mov_b64 s[16:17], -1
	v_mul_f32_e32 v39, v198, v47
	v_mul_f32_e32 v0, v199, v41
	s_cbranch_vccnz .LBB0_335
	v_bfe_u32 v41, v39, 16, 1
	v_lshlrev_b64 v[74:75], 10, v[64:65]
	v_add3_u32 v41, v39, v41, s2
	v_lshl_add_u64 v[74:75], v[54:55], 0, v[74:75]
	v_ashrrev_i32_e32 v67, 31, v66
	global_store_short_d16_hi v[74:75], v41, off
	v_bfe_u32 v41, v0, 16, 1
	v_lshlrev_b64 v[66:67], 11, v[66:67]
	v_add3_u32 v41, v0, v41, s2
	v_lshl_add_u64 v[66:67], v[52:53], 0, v[66:67]
	s_mov_b64 s[16:17], 0
	global_store_short_d16_hi v[74:75], v41, off offset:64
	global_store_dword v[66:67], v39, off
	global_store_dword v[66:67], v0, off offset:128

; __device__ __forceinline__ unsigned f2bf(float f) { unsigned u = __builtin_bit_cast(unsigned, f); return (u + 0x7fffu + ((u >> 16) & 1u)) >> 16; }
;     __device__ __forceinline__ void operator()(const f32x16& acc0, const f32x16& acc1, int rb, int cg, int r32, int hi, const float (&ss)[16]) const {
;     ...
;             } else if (pn < 10) {
;                 float q = v0 * v0 + v1 * v1;
;                 q += __shfl_xor(q, 1); q += __shfl_xor(q, 2); q += __shfl_xor(q, 4); q += __shfl_xor(q, 8); q += __shfl_xor(q, 16);
;                 const float rn = rsqrtf(q * (1.0f / 64.0f) + EPS);
;                 const bool isq = pn < 8;
;                 const float* gp = isq ? qg : kg;
;                 const int col = ((pn & 1) * 4 + hd) * 64 + r32;
;                 const float a0 = v0 * rn * gp[r32], a1 = v1 * rn * gp[32 + r32];
;                 if (isq) { bf16_t* SQ = (bf16_t*)(ws + WS_SQ); SQ[(size_t)row * 512 + col] = (bf16_t)f2bf(a0 * QSCALE); SQ[(size_t)row * 512 + col + 32] = (bf16_t)f2bf(a1 * QSCALE); }
;                 else { bf16_t* KB = (bf16_t*)(ws + WS_KB); KB[(size_t)row * 512 + col] = (bf16_t)f2bf(a0); KB[(size_t)row * 512 + col + 32] = (bf16_t)f2bf(a1);
;                     Ks[(size_t)rs_ * 512 + col] = a0; Ks[(size_t)rs_ * 512 + col + 32] = a1; }
.LBB0_348:
	s_andn2_b64 vcc, exec, s[16:17]
	s_cbranch_vccnz .LBB0_353
	s_and_b64 s[16:17], s[44:45], exec
	s_cselect_b32 s17, s62, s64
	s_cselect_b32 s16, s61, s63
	v_lshlrev_b32_e32 v0, 2, v98
	s_nop 0
	v_pk_mul_f32 v[74:75], v[62:63], v[62:63]
	v_xor_b32_e32 v49, 16, v205
	v_add_f32_e32 v41, v74, v75
	ds_bpermute_b32 v47, v69, v41
	v_cmp_lt_i32_e32 vcc, v49, v68
	s_waitcnt lgkmcnt(0)
	v_add_f32_e32 v41, v41, v47
	ds_bpermute_b32 v47, v70, v41
	v_cndmask_b32_e32 v49, v205, v49, vcc
	v_lshlrev_b32_e32 v49, 2, v49
	s_andn2_b64 vcc, exec, s[42:43]
	s_waitcnt lgkmcnt(0)
	v_add_f32_e32 v41, v41, v47
	ds_bpermute_b32 v47, v71, v41
	s_waitcnt lgkmcnt(0)
	v_add_f32_e32 v41, v41, v47
	ds_bpermute_b32 v47, v72, v41
	s_waitcnt lgkmcnt(0)
	v_add_f32_e32 v41, v41, v47
	ds_bpermute_b32 v47, v49, v41
	s_waitcnt lgkmcnt(0)
	v_add_f32_e32 v41, v41, v47
	v_fmamk_f32 v41, v41, 0x3c800000, v201
	v_mul_f32_e32 v47, 0x4b800000, v41
	v_cmp_gt_f32_e64 s[16:17], s3, v41
	s_nop 1
	v_cndmask_b32_e64 v41, v41, v47, s[16:17]
	v_rsq_f32_e32 v41, v41
	s_nop 0
	v_mul_f32_e32 v47, 0x45800000, v41
	v_cndmask_b32_e64 v41, v41, v47, s[16:17]
	v_mul_f32_e32 v47, v62, v41
	v_mul_f32_e32 v41, v63, v41
	s_mov_b64 s[16:17], -1
	v_mul_f32_e32 v39, v198, v47
	v_mul_f32_e32 v0, v199, v41
	s_cbranch_vccnz .LBB0_351
	v_bfe_u32 v41, v39, 16, 1
	v_lshlrev_b64 v[74:75], 10, v[64:65]
	v_add3_u32 v41, v39, v41, s2
	v_lshl_add_u64 v[74:75], v[54:55], 0, v[74:75]
	v_ashrrev_i32_e32 v67, 31, v66
	global_store_short_d16_hi v[74:75], v41, off
	v_bfe_u32 v41, v0, 16, 1
	v_lshlrev_b64 v[66:67], 11, v[66:67]
	v_add3_u32 v41, v0, v41, s2
	v_lshl_add_u64 v[66:67], v[52:53], 0, v[66:67]
	s_mov_b64 s[16:17], 0
	global_store_short_d16_hi v[74:75], v41, off offset:64
	global_store_dword v[66:67], v39, off
	global_store_dword v[66:67], v0, off offset:128

; __device__ __forceinline__ unsigned f2bf(float f) { unsigned u = __builtin_bit_cast(unsigned, f); return (u + 0x7fffu + ((u >> 16) & 1u)) >> 16; }
;     __device__ __forceinline__ void operator()(const f32x16& acc0, const f32x16& acc1, int rb, int cg, int r32, int hi, const float (&ss)[16]) const {
;     ...
;             } else if (pn < 10) {
;                 float q = v0 * v0 + v1 * v1;
;                 q += __shfl_xor(q, 1); q += __shfl_xor(q, 2); q += __shfl_xor(q, 4); q += __shfl_xor(q, 8); q += __shfl_xor(q, 16);
;                 const float rn = rsqrtf(q * (1.0f / 64.0f) + EPS);
;                 const bool isq = pn < 8;
;                 const float* gp = isq ? qg : kg;
;                 const int col = ((pn & 1) * 4 + hd) * 64 + r32;
;                 const float a0 = v0 * rn * gp[r32], a1 = v1 * rn * gp[32 + r32];
;                 if (isq) { bf16_t* SQ = (bf16_t*)(ws + WS_SQ); SQ[(size_t)row * 512 + col] = (bf16_t)f2bf(a0 * QSCALE); SQ[(size_t)row * 512 + col + 32] = (bf16_t)f2bf(a1 * QSCALE); }
;                 else { bf16_t* KB = (bf16_t*)(ws + WS_KB); KB[(size_t)row * 512 + col] = (bf16_t)f2bf(a0); KB[(size_t)row * 512 + col + 32] = (bf16_t)f2bf(a1);
;                     Ks[(size_t)rs_ * 512 + col] = a0; Ks[(size_t)rs_ * 512 + col + 32] = a1; }
.LBB0_364:
	s_andn2_b64 vcc, exec, s[16:17]
	s_cbranch_vccnz .LBB0_369
	s_and_b64 s[16:17], s[44:45], exec
	s_cselect_b32 s17, s62, s64
	s_cselect_b32 s16, s61, s63
	v_lshlrev_b32_e32 v0, 2, v98
	s_nop 0
	v_pk_mul_f32 v[74:75], v[62:63], v[62:63]
	v_xor_b32_e32 v47, 16, v205
	v_add_f32_e32 v41, v74, v75
	ds_bpermute_b32 v43, v69, v41
	v_cmp_lt_i32_e32 vcc, v47, v68
	s_waitcnt lgkmcnt(0)
	v_add_f32_e32 v41, v41, v43
	ds_bpermute_b32 v43, v70, v41
	v_cndmask_b32_e32 v47, v205, v47, vcc
	v_lshlrev_b32_e32 v47, 2, v47
	s_andn2_b64 vcc, exec, s[42:43]
	s_waitcnt lgkmcnt(0)
	v_add_f32_e32 v41, v41, v43
	ds_bpermute_b32 v43, v71, v41
	s_waitcnt lgkmcnt(0)
	v_add_f32_e32 v41, v41, v43
	ds_bpermute_b32 v43, v72, v41
	s_waitcnt lgkmcnt(0)
	v_add_f32_e32 v41, v41, v43
	ds_bpermute_b32 v43, v47, v41
	s_waitcnt lgkmcnt(0)
	v_add_f32_e32 v41, v41, v43
	v_fmamk_f32 v41, v41, 0x3c800000, v201
	v_mul_f32_e32 v43, 0x4b800000, v41
	v_cmp_gt_f32_e64 s[16:17], s3, v41
	s_nop 1
	v_cndmask_b32_e64 v41, v41, v43, s[16:17]
	v_rsq_f32_e32 v41, v41
	s_nop 0
	v_mul_f32_e32 v43, 0x45800000, v41
	v_cndmask_b32_e64 v41, v41, v43, s[16:17]
	v_mul_f32_e32 v43, v62, v41
	v_mul_f32_e32 v41, v63, v41
	s_mov_b64 s[16:17], -1
	v_mul_f32_e32 v39, v198, v43
	v_mul_f32_e32 v0, v199, v41
	s_cbranch_vccnz .LBB0_367
	v_bfe_u32 v41, v39, 16, 1
	v_lshlrev_b64 v[74:75], 10, v[64:65]
	v_add3_u32 v41, v39, v41, s2
	v_lshl_add_u64 v[74:75], v[54:55], 0, v[74:75]
	v_ashrrev_i32_e32 v67, 31, v66
	global_store_short_d16_hi v[74:75], v41, off
	v_bfe_u32 v41, v0, 16, 1
	v_lshlrev_b64 v[66:67], 11, v[66:67]
	v_add3_u32 v41, v0, v41, s2
	v_lshl_add_u64 v[66:67], v[52:53], 0, v[66:67]
	s_mov_b64 s[16:17], 0
	global_store_short_d16_hi v[74:75], v41, off offset:64
	global_store_dword v[66:67], v39, off
	global_store_dword v[66:67], v0, off offset:128

; __device__ __forceinline__ unsigned f2bf(float f) { unsigned u = __builtin_bit_cast(unsigned, f); return (u + 0x7fffu + ((u >> 16) & 1u)) >> 16; }
;     __device__ __forceinline__ void operator()(const f32x16& acc0, const f32x16& acc1, int rb, int cg, int r32, int hi, const float (&ss)[16]) const {
;     ...
;             } else if (pn < 10) {
;                 float q = v0 * v0 + v1 * v1;
;                 q += __shfl_xor(q, 1); q += __shfl_xor(q, 2); q += __shfl_xor(q, 4); q += __shfl_xor(q, 8); q += __shfl_xor(q, 16);
;                 const float rn = rsqrtf(q * (1.0f / 64.0f) + EPS);
;                 const bool isq = pn < 8;
;                 const float* gp = isq ? qg : kg;
;                 const int col = ((pn & 1) * 4 + hd) * 64 + r32;
;                 const float a0 = v0 * rn * gp[r32], a1 = v1 * rn * gp[32 + r32];
;                 if (isq) { bf16_t* SQ = (bf16_t*)(ws + WS_SQ); SQ[(size_t)row * 512 + col] = (bf16_t)f2bf(a0 * QSCALE); SQ[(size_t)row * 512 + col + 32] = (bf16_t)f2bf(a1 * QSCALE); }
;                 else { bf16_t* KB = (bf16_t*)(ws + WS_KB); KB[(size_t)row * 512 + col] = (bf16_t)f2bf(a0); KB[(size_t)row * 512 + col + 32] = (bf16_t)f2bf(a1);
;                     Ks[(size_t)rs_ * 512 + col] = a0; Ks[(size_t)rs_ * 512 + col + 32] = a1; }
.LBB0_380:
	s_andn2_b64 vcc, exec, s[16:17]
	s_cbranch_vccnz .LBB0_385
	s_and_b64 s[16:17], s[44:45], exec
	s_cselect_b32 s17, s62, s64
	s_cselect_b32 s16, s61, s63
	v_lshlrev_b32_e32 v0, 2, v98
	s_nop 0
	v_pk_mul_f32 v[74:75], v[62:63], v[62:63]
	v_xor_b32_e32 v45, 16, v205
	v_add_f32_e32 v41, v74, v75
	ds_bpermute_b32 v43, v69, v41
	v_cmp_lt_i32_e32 vcc, v45, v68
	s_waitcnt lgkmcnt(0)
	v_add_f32_e32 v41, v41, v43
	ds_bpermute_b32 v43, v70, v41
	v_cndmask_b32_e32 v45, v205, v45, vcc
	v_lshlrev_b32_e32 v45, 2, v45
	s_andn2_b64 vcc, exec, s[42:43]
	s_waitcnt lgkmcnt(0)
	v_add_f32_e32 v41, v41, v43
	ds_bpermute_b32 v43, v71, v41
	s_waitcnt lgkmcnt(0)
	v_add_f32_e32 v41, v41, v43
	ds_bpermute_b32 v43, v72, v41
	s_waitcnt lgkmcnt(0)
	v_add_f32_e32 v41, v41, v43
	ds_bpermute_b32 v43, v45, v41
	s_waitcnt lgkmcnt(0)
	v_add_f32_e32 v41, v41, v43
	v_fmamk_f32 v41, v41, 0x3c800000, v201
	v_mul_f32_e32 v43, 0x4b800000, v41
	v_cmp_gt_f32_e64 s[16:17], s3, v41
	s_nop 1
	v_cndmask_b32_e64 v41, v41, v43, s[16:17]
	v_rsq_f32_e32 v41, v41
	s_nop 0
	v_mul_f32_e32 v43, 0x45800000, v41
	v_cndmask_b32_e64 v41, v41, v43, s[16:17]
	v_mul_f32_e32 v43, v62, v41
	v_mul_f32_e32 v41, v63, v41
	s_mov_b64 s[16:17], -1
	v_mul_f32_e32 v39, v198, v43
	v_mul_f32_e32 v0, v199, v41
	s_cbranch_vccnz .LBB0_383
	v_bfe_u32 v41, v39, 16, 1
	v_lshlrev_b64 v[74:75], 10, v[64:65]
	v_add3_u32 v41, v39, v41, s2
	v_lshl_add_u64 v[74:75], v[54:55], 0, v[74:75]
	v_ashrrev_i32_e32 v67, 31, v66
	global_store_short_d16_hi v[74:75], v41, off
	v_bfe_u32 v41, v0, 16, 1
	v_lshlrev_b64 v[66:67], 11, v[66:67]
	v_add3_u32 v41, v0, v41, s2
	v_lshl_add_u64 v[66:67], v[52:53], 0, v[66:67]
	s_mov_b64 s[16:17], 0
	global_store_short_d16_hi v[74:75], v41, off offset:64
	global_store_dword v[66:67], v39, off
	global_store_dword v[66:67], v0, off offset:128

; __device__ __forceinline__ unsigned f2bf(float f) { unsigned u = __builtin_bit_cast(unsigned, f); return (u + 0x7fffu + ((u >> 16) & 1u)) >> 16; }
;     __device__ __forceinline__ void operator()(const f32x16& acc0, const f32x16& acc1, int rb, int cg, int r32, int hi, const float (&ss)[16]) const {
;     ...
;             } else if (pn < 10) {
;                 float q = v0 * v0 + v1 * v1;
;                 q += __shfl_xor(q, 1); q += __shfl_xor(q, 2); q += __shfl_xor(q, 4); q += __shfl_xor(q, 8); q += __shfl_xor(q, 16);
;                 const float rn = rsqrtf(q * (1.0f / 64.0f) + EPS);
;                 const bool isq = pn < 8;
;                 const float* gp = isq ? qg : kg;
;                 const int col = ((pn & 1) * 4 + hd) * 64 + r32;
;                 const float a0 = v0 * rn * gp[r32], a1 = v1 * rn * gp[32 + r32];
;                 if (isq) { bf16_t* SQ = (bf16_t*)(ws + WS_SQ); SQ[(size_t)row * 512 + col] = (bf16_t)f2bf(a0 * QSCALE); SQ[(size_t)row * 512 + col + 32] = (bf16_t)f2bf(a1 * QSCALE); }
;                 else { bf16_t* KB = (bf16_t*)(ws + WS_KB); KB[(size_t)row * 512 + col] = (bf16_t)f2bf(a0); KB[(size_t)row * 512 + col + 32] = (bf16_t)f2bf(a1);
;                     Ks[(size_t)rs_ * 512 + col] = a0; Ks[(size_t)rs_ * 512 + col + 32] = a1; }
.LBB0_396:
	s_andn2_b64 vcc, exec, s[16:17]
	s_cbranch_vccnz .LBB0_401
	s_and_b64 s[16:17], s[44:45], exec
	s_cselect_b32 s17, s62, s64
	s_cselect_b32 s16, s61, s63
	v_lshlrev_b32_e32 v0, 2, v98
	s_nop 0
	v_pk_mul_f32 v[74:75], v[62:63], v[62:63]
	v_xor_b32_e32 v43, 16, v205
	v_add_f32_e32 v39, v74, v75
	ds_bpermute_b32 v41, v69, v39
	v_cmp_lt_i32_e32 vcc, v43, v68
	s_waitcnt lgkmcnt(0)
	v_add_f32_e32 v39, v39, v41
	ds_bpermute_b32 v41, v70, v39
	v_cndmask_b32_e32 v43, v205, v43, vcc
	v_lshlrev_b32_e32 v43, 2, v43
	s_andn2_b64 vcc, exec, s[42:43]
	s_waitcnt lgkmcnt(0)
	v_add_f32_e32 v39, v39, v41
	ds_bpermute_b32 v41, v71, v39
	s_waitcnt lgkmcnt(0)
	v_add_f32_e32 v39, v39, v41
	ds_bpermute_b32 v41, v72, v39
	s_waitcnt lgkmcnt(0)
	v_add_f32_e32 v39, v39, v41
	ds_bpermute_b32 v41, v43, v39
	s_waitcnt lgkmcnt(0)
	v_add_f32_e32 v39, v39, v41
	v_fmamk_f32 v39, v39, 0x3c800000, v201
	v_mul_f32_e32 v41, 0x4b800000, v39
	v_cmp_gt_f32_e64 s[16:17], s3, v39
	s_nop 1
	v_cndmask_b32_e64 v39, v39, v41, s[16:17]
	v_rsq_f32_e32 v39, v39
	s_nop 0
	v_mul_f32_e32 v41, 0x45800000, v39
	v_cndmask_b32_e64 v39, v39, v41, s[16:17]
	v_mul_f32_e32 v41, v62, v39
	v_mul_f32_e32 v39, v63, v39
	s_mov_b64 s[16:17], -1
	v_mul_f32_e32 v35, v198, v41
	v_mul_f32_e32 v0, v199, v39
	s_cbranch_vccnz .LBB0_399
	v_bfe_u32 v39, v35, 16, 1
	v_lshlrev_b64 v[74:75], 10, v[64:65]
	v_add3_u32 v39, v35, v39, s2
	v_lshl_add_u64 v[74:75], v[54:55], 0, v[74:75]
	v_ashrrev_i32_e32 v67, 31, v66
	global_store_short_d16_hi v[74:75], v39, off
	v_bfe_u32 v39, v0, 16, 1
	v_lshlrev_b64 v[66:67], 11, v[66:67]
	v_add3_u32 v39, v0, v39, s2
	v_lshl_add_u64 v[66:67], v[52:53], 0, v[66:67]
	s_mov_b64 s[16:17], 0
	global_store_short_d16_hi v[74:75], v39, off offset:64
	global_store_dword v[66:67], v35, off
	global_store_dword v[66:67], v0, off offset:128

; __device__ __forceinline__ unsigned f2bf(float f) { unsigned u = __builtin_bit_cast(unsigned, f); return (u + 0x7fffu + ((u >> 16) & 1u)) >> 16; }
;     __device__ __forceinline__ void operator()(const f32x16& acc0, const f32x16& acc1, int rb, int cg, int r32, int hi, const float (&ss)[16]) const {
;     ...
;             } else if (pn < 10) {
;                 float q = v0 * v0 + v1 * v1;
;                 q += __shfl_xor(q, 1); q += __shfl_xor(q, 2); q += __shfl_xor(q, 4); q += __shfl_xor(q, 8); q += __shfl_xor(q, 16);
;                 const float rn = rsqrtf(q * (1.0f / 64.0f) + EPS);
;                 const bool isq = pn < 8;
;                 const float* gp = isq ? qg : kg;
;                 const int col = ((pn & 1) * 4 + hd) * 64 + r32;
;                 const float a0 = v0 * rn * gp[r32], a1 = v1 * rn * gp[32 + r32];
;                 if (isq) { bf16_t* SQ = (bf16_t*)(ws + WS_SQ); SQ[(size_t)row * 512 + col] = (bf16_t)f2bf(a0 * QSCALE); SQ[(size_t)row * 512 + col + 32] = (bf16_t)f2bf(a1 * QSCALE); }
;                 else { bf16_t* KB = (bf16_t*)(ws + WS_KB); KB[(size_t)row * 512 + col] = (bf16_t)f2bf(a0); KB[(size_t)row * 512 + col + 32] = (bf16_t)f2bf(a1);
;                     Ks[(size_t)rs_ * 512 + col] = a0; Ks[(size_t)rs_ * 512 + col + 32] = a1; }
.LBB0_412:
	s_andn2_b64 vcc, exec, s[16:17]
	s_cbranch_vccnz .LBB0_417
	s_and_b64 s[16:17], s[44:45], exec
	s_cselect_b32 s17, s62, s64
	s_cselect_b32 s16, s61, s63
	v_lshlrev_b32_e32 v0, 2, v98
	s_nop 0
	v_pk_mul_f32 v[74:75], v[62:63], v[62:63]
	v_xor_b32_e32 v41, 16, v205
	v_add_f32_e32 v35, v74, v75
	ds_bpermute_b32 v39, v69, v35
	v_cmp_lt_i32_e32 vcc, v41, v68
	s_waitcnt lgkmcnt(0)
	v_add_f32_e32 v35, v35, v39
	ds_bpermute_b32 v39, v70, v35
	v_cndmask_b32_e32 v41, v205, v41, vcc
	v_lshlrev_b32_e32 v41, 2, v41
	s_andn2_b64 vcc, exec, s[42:43]
	s_waitcnt lgkmcnt(0)
	v_add_f32_e32 v35, v35, v39
	ds_bpermute_b32 v39, v71, v35
	s_waitcnt lgkmcnt(0)
	v_add_f32_e32 v35, v35, v39
	ds_bpermute_b32 v39, v72, v35
	s_waitcnt lgkmcnt(0)
	v_add_f32_e32 v35, v35, v39
	ds_bpermute_b32 v39, v41, v35
	s_waitcnt lgkmcnt(0)
	v_add_f32_e32 v35, v35, v39
	v_fmamk_f32 v35, v35, 0x3c800000, v201
	v_mul_f32_e32 v39, 0x4b800000, v35
	v_cmp_gt_f32_e64 s[16:17], s3, v35
	s_nop 1
	v_cndmask_b32_e64 v35, v35, v39, s[16:17]
	v_rsq_f32_e32 v35, v35
	s_nop 0
	v_mul_f32_e32 v39, 0x45800000, v35
	v_cndmask_b32_e64 v35, v35, v39, s[16:17]
	v_mul_f32_e32 v39, v62, v35
	v_mul_f32_e32 v35, v63, v35
	s_mov_b64 s[16:17], -1
	v_mul_f32_e32 v33, v198, v39
	v_mul_f32_e32 v0, v199, v35
	s_cbranch_vccnz .LBB0_415
	v_bfe_u32 v35, v33, 16, 1
	v_lshlrev_b64 v[74:75], 10, v[64:65]
	v_add3_u32 v35, v33, v35, s2
	v_lshl_add_u64 v[74:75], v[54:55], 0, v[74:75]
	v_ashrrev_i32_e32 v67, 31, v66
	global_store_short_d16_hi v[74:75], v35, off
	v_bfe_u32 v35, v0, 16, 1
	v_lshlrev_b64 v[66:67], 11, v[66:67]
	v_add3_u32 v35, v0, v35, s2
	v_lshl_add_u64 v[66:67], v[52:53], 0, v[66:67]
	s_mov_b64 s[16:17], 0
	global_store_short_d16_hi v[74:75], v35, off offset:64
	global_store_dword v[66:67], v33, off
	global_store_dword v[66:67], v0, off offset:128

; __device__ __forceinline__ unsigned f2bf(float f) { unsigned u = __builtin_bit_cast(unsigned, f); return (u + 0x7fffu + ((u >> 16) & 1u)) >> 16; }
;     __device__ __forceinline__ void operator()(const f32x16& acc0, const f32x16& acc1, int rb, int cg, int r32, int hi, const float (&ss)[16]) const {
;     ...
;             } else if (pn < 10) {
;                 float q = v0 * v0 + v1 * v1;
;                 q += __shfl_xor(q, 1); q += __shfl_xor(q, 2); q += __shfl_xor(q, 4); q += __shfl_xor(q, 8); q += __shfl_xor(q, 16);
;                 const float rn = rsqrtf(q * (1.0f / 64.0f) + EPS);
;                 const bool isq = pn < 8;
;                 const float* gp = isq ? qg : kg;
;                 const int col = ((pn & 1) * 4 + hd) * 64 + r32;
;                 const float a0 = v0 * rn * gp[r32], a1 = v1 * rn * gp[32 + r32];
;                 if (isq) { bf16_t* SQ = (bf16_t*)(ws + WS_SQ); SQ[(size_t)row * 512 + col] = (bf16_t)f2bf(a0 * QSCALE); SQ[(size_t)row * 512 + col + 32] = (bf16_t)f2bf(a1 * QSCALE); }
;                 else { bf16_t* KB = (bf16_t*)(ws + WS_KB); KB[(size_t)row * 512 + col] = (bf16_t)f2bf(a0); KB[(size_t)row * 512 + col + 32] = (bf16_t)f2bf(a1);
;                     Ks[(size_t)rs_ * 512 + col] = a0; Ks[(size_t)rs_ * 512 + col + 32] = a1; }
.LBB0_428:
	s_andn2_b64 vcc, exec, s[16:17]
	s_cbranch_vccnz .LBB0_433
	s_and_b64 s[16:17], s[44:45], exec
	s_cselect_b32 s17, s62, s64
	s_cselect_b32 s16, s61, s63
	v_lshlrev_b32_e32 v0, 2, v98
	s_nop 0
	v_pk_mul_f32 v[74:75], v[62:63], v[62:63]
	v_xor_b32_e32 v39, 16, v205
	v_add_f32_e32 v33, v74, v75
	ds_bpermute_b32 v35, v69, v33
	v_cmp_lt_i32_e32 vcc, v39, v68
	s_waitcnt lgkmcnt(0)
	v_add_f32_e32 v33, v33, v35
	ds_bpermute_b32 v35, v70, v33
	v_cndmask_b32_e32 v39, v205, v39, vcc
	v_lshlrev_b32_e32 v39, 2, v39
	s_andn2_b64 vcc, exec, s[42:43]
	s_waitcnt lgkmcnt(0)
	v_add_f32_e32 v33, v33, v35
	ds_bpermute_b32 v35, v71, v33
	s_waitcnt lgkmcnt(0)
	v_add_f32_e32 v33, v33, v35
	ds_bpermute_b32 v35, v72, v33
	s_waitcnt lgkmcnt(0)
	v_add_f32_e32 v33, v33, v35
	ds_bpermute_b32 v35, v39, v33
	s_waitcnt lgkmcnt(0)
	v_add_f32_e32 v33, v33, v35
	v_fmamk_f32 v33, v33, 0x3c800000, v201
	v_mul_f32_e32 v35, 0x4b800000, v33
	v_cmp_gt_f32_e64 s[16:17], s3, v33
	s_nop 1
	v_cndmask_b32_e64 v33, v33, v35, s[16:17]
	v_rsq_f32_e32 v33, v33
	s_nop 0
	v_mul_f32_e32 v35, 0x45800000, v33
	v_cndmask_b32_e64 v33, v33, v35, s[16:17]
	v_mul_f32_e32 v35, v62, v33
	v_mul_f32_e32 v33, v63, v33
	s_mov_b64 s[16:17], -1
	v_mul_f32_e32 v27, v198, v35
	v_mul_f32_e32 v0, v199, v33
	s_cbranch_vccnz .LBB0_431
	v_bfe_u32 v33, v27, 16, 1
	v_lshlrev_b64 v[74:75], 10, v[64:65]
	v_add3_u32 v33, v27, v33, s2
	v_lshl_add_u64 v[74:75], v[54:55], 0, v[74:75]
	v_ashrrev_i32_e32 v67, 31, v66
	global_store_short_d16_hi v[74:75], v33, off
	v_bfe_u32 v33, v0, 16, 1
	v_lshlrev_b64 v[66:67], 11, v[66:67]
	v_add3_u32 v33, v0, v33, s2
	v_lshl_add_u64 v[66:67], v[52:53], 0, v[66:67]
	s_mov_b64 s[16:17], 0
	global_store_short_d16_hi v[74:75], v33, off offset:64
	global_store_dword v[66:67], v27, off
	global_store_dword v[66:67], v0, off offset:128

; __device__ __forceinline__ unsigned f2bf(float f) { unsigned u = __builtin_bit_cast(unsigned, f); return (u + 0x7fffu + ((u >> 16) & 1u)) >> 16; }
;     __device__ __forceinline__ void operator()(const f32x16& acc0, const f32x16& acc1, int rb, int cg, int r32, int hi, const float (&ss)[16]) const {
;     ...
;             } else if (pn < 10) {
;                 float q = v0 * v0 + v1 * v1;
;                 q += __shfl_xor(q, 1); q += __shfl_xor(q, 2); q += __shfl_xor(q, 4); q += __shfl_xor(q, 8); q += __shfl_xor(q, 16);
;                 const float rn = rsqrtf(q * (1.0f / 64.0f) + EPS);
;                 const bool isq = pn < 8;
;                 const float* gp = isq ? qg : kg;
;                 const int col = ((pn & 1) * 4 + hd) * 64 + r32;
;                 const float a0 = v0 * rn * gp[r32], a1 = v1 * rn * gp[32 + r32];
;                 if (isq) { bf16_t* SQ = (bf16_t*)(ws + WS_SQ); SQ[(size_t)row * 512 + col] = (bf16_t)f2bf(a0 * QSCALE); SQ[(size_t)row * 512 + col + 32] = (bf16_t)f2bf(a1 * QSCALE); }
;                 else { bf16_t* KB = (bf16_t*)(ws + WS_KB); KB[(size_t)row * 512 + col] = (bf16_t)f2bf(a0); KB[(size_t)row * 512 + col + 32] = (bf16_t)f2bf(a1);
;                     Ks[(size_t)rs_ * 512 + col] = a0; Ks[(size_t)rs_ * 512 + col + 32] = a1; }
.LBB0_444:
	s_andn2_b64 vcc, exec, s[16:17]
	s_cbranch_vccnz .LBB0_449
	s_and_b64 s[16:17], s[44:45], exec
	s_cselect_b32 s17, s62, s64
	s_cselect_b32 s16, s61, s63
	v_lshlrev_b32_e32 v0, 2, v98
	s_nop 0
	v_pk_mul_f32 v[74:75], v[62:63], v[62:63]
	v_xor_b32_e32 v35, 16, v205
	v_add_f32_e32 v29, v74, v75
	ds_bpermute_b32 v33, v69, v29
	v_cmp_lt_i32_e32 vcc, v35, v68
	s_waitcnt lgkmcnt(0)
	v_add_f32_e32 v29, v29, v33
	ds_bpermute_b32 v33, v70, v29
	v_cndmask_b32_e32 v35, v205, v35, vcc
	v_lshlrev_b32_e32 v35, 2, v35
	s_andn2_b64 vcc, exec, s[42:43]
	s_waitcnt lgkmcnt(0)
	v_add_f32_e32 v29, v29, v33
	ds_bpermute_b32 v33, v71, v29
	s_waitcnt lgkmcnt(0)
	v_add_f32_e32 v29, v29, v33
	ds_bpermute_b32 v33, v72, v29
	s_waitcnt lgkmcnt(0)
	v_add_f32_e32 v29, v29, v33
	ds_bpermute_b32 v33, v35, v29
	s_waitcnt lgkmcnt(0)
	v_add_f32_e32 v29, v29, v33
	v_fmamk_f32 v29, v29, 0x3c800000, v201
	v_mul_f32_e32 v33, 0x4b800000, v29
	v_cmp_gt_f32_e64 s[16:17], s3, v29
	s_nop 1
	v_cndmask_b32_e64 v29, v29, v33, s[16:17]
	v_rsq_f32_e32 v29, v29
	s_nop 0
	v_mul_f32_e32 v33, 0x45800000, v29
	v_cndmask_b32_e64 v29, v29, v33, s[16:17]
	v_mul_f32_e32 v33, v62, v29
	v_mul_f32_e32 v29, v63, v29
	s_mov_b64 s[16:17], -1
	v_mul_f32_e32 v27, v198, v33
	v_mul_f32_e32 v0, v199, v29
	s_cbranch_vccnz .LBB0_447
	v_bfe_u32 v29, v27, 16, 1
	v_lshlrev_b64 v[74:75], 10, v[64:65]
	v_add3_u32 v29, v27, v29, s2
	v_lshl_add_u64 v[74:75], v[54:55], 0, v[74:75]
	v_ashrrev_i32_e32 v67, 31, v66
	global_store_short_d16_hi v[74:75], v29, off
	v_bfe_u32 v29, v0, 16, 1
	v_lshlrev_b64 v[66:67], 11, v[66:67]
	v_add3_u32 v29, v0, v29, s2
	v_lshl_add_u64 v[66:67], v[52:53], 0, v[66:67]
	s_mov_b64 s[16:17], 0
	global_store_short_d16_hi v[74:75], v29, off offset:64
	global_store_dword v[66:67], v27, off
	global_store_dword v[66:67], v0, off offset:128

; __device__ __forceinline__ unsigned f2bf(float f) { unsigned u = __builtin_bit_cast(unsigned, f); return (u + 0x7fffu + ((u >> 16) & 1u)) >> 16; }
;     __device__ __forceinline__ void operator()(const f32x16& acc0, const f32x16& acc1, int rb, int cg, int r32, int hi, const float (&ss)[16]) const {
;     ...
;             } else if (pn < 10) {
;                 float q = v0 * v0 + v1 * v1;
;                 q += __shfl_xor(q, 1); q += __shfl_xor(q, 2); q += __shfl_xor(q, 4); q += __shfl_xor(q, 8); q += __shfl_xor(q, 16);
;                 const float rn = rsqrtf(q * (1.0f / 64.0f) + EPS);
;                 const bool isq = pn < 8;
;                 const float* gp = isq ? qg : kg;
;                 const int col = ((pn & 1) * 4 + hd) * 64 + r32;
;                 const float a0 = v0 * rn * gp[r32], a1 = v1 * rn * gp[32 + r32];
;                 if (isq) { bf16_t* SQ = (bf16_t*)(ws + WS_SQ); SQ[(size_t)row * 512 + col] = (bf16_t)f2bf(a0 * QSCALE); SQ[(size_t)row * 512 + col + 32] = (bf16_t)f2bf(a1 * QSCALE); }
;                 else { bf16_t* KB = (bf16_t*)(ws + WS_KB); KB[(size_t)row * 512 + col] = (bf16_t)f2bf(a0); KB[(size_t)row * 512 + col + 32] = (bf16_t)f2bf(a1);
;                     Ks[(size_t)rs_ * 512 + col] = a0; Ks[(size_t)rs_ * 512 + col + 32] = a1; }
.LBB0_460:
	s_andn2_b64 vcc, exec, s[16:17]
	s_cbranch_vccnz .LBB0_465
	s_and_b64 s[16:17], s[44:45], exec
	s_cselect_b32 s17, s62, s64
	s_cselect_b32 s16, s61, s63
	v_lshlrev_b32_e32 v0, 2, v98
	s_nop 0
	v_pk_mul_f32 v[74:75], v[62:63], v[62:63]
	v_xor_b32_e32 v33, 16, v205
	v_add_f32_e32 v27, v74, v75
	ds_bpermute_b32 v29, v69, v27
	v_cmp_lt_i32_e32 vcc, v33, v68
	s_waitcnt lgkmcnt(0)
	v_add_f32_e32 v27, v27, v29
	ds_bpermute_b32 v29, v70, v27
	v_cndmask_b32_e32 v33, v205, v33, vcc
	v_lshlrev_b32_e32 v33, 2, v33
	s_andn2_b64 vcc, exec, s[42:43]
	s_waitcnt lgkmcnt(0)
	v_add_f32_e32 v27, v27, v29
	ds_bpermute_b32 v29, v71, v27
	s_waitcnt lgkmcnt(0)
	v_add_f32_e32 v27, v27, v29
	ds_bpermute_b32 v29, v72, v27
	s_waitcnt lgkmcnt(0)
	v_add_f32_e32 v27, v27, v29
	ds_bpermute_b32 v29, v33, v27
	s_waitcnt lgkmcnt(0)
	v_add_f32_e32 v27, v27, v29
	v_fmamk_f32 v27, v27, 0x3c800000, v201
	v_mul_f32_e32 v29, 0x4b800000, v27
	v_cmp_gt_f32_e64 s[16:17], s3, v27
	s_nop 1
	v_cndmask_b32_e64 v27, v27, v29, s[16:17]
	v_rsq_f32_e32 v27, v27
	s_nop 0
	v_mul_f32_e32 v29, 0x45800000, v27
	v_cndmask_b32_e64 v27, v27, v29, s[16:17]
	v_mul_f32_e32 v29, v62, v27
	v_mul_f32_e32 v27, v63, v27
	s_mov_b64 s[16:17], -1
	v_mul_f32_e32 v23, v198, v29
	v_mul_f32_e32 v0, v199, v27
	s_cbranch_vccnz .LBB0_463
	v_bfe_u32 v27, v23, 16, 1
	v_lshlrev_b64 v[74:75], 10, v[64:65]
	v_add3_u32 v27, v23, v27, s2
	v_lshl_add_u64 v[74:75], v[54:55], 0, v[74:75]
	v_ashrrev_i32_e32 v67, 31, v66
	global_store_short_d16_hi v[74:75], v27, off
	v_bfe_u32 v27, v0, 16, 1
	v_lshlrev_b64 v[66:67], 11, v[66:67]
	v_add3_u32 v27, v0, v27, s2
	v_lshl_add_u64 v[66:67], v[52:53], 0, v[66:67]
	s_mov_b64 s[16:17], 0
	global_store_short_d16_hi v[74:75], v27, off offset:64
	global_store_dword v[66:67], v23, off
	global_store_dword v[66:67], v0, off offset:128

; __device__ __forceinline__ unsigned f2bf(float f) { unsigned u = __builtin_bit_cast(unsigned, f); return (u + 0x7fffu + ((u >> 16) & 1u)) >> 16; }
;     __device__ __forceinline__ void operator()(const f32x16& acc0, const f32x16& acc1, int rb, int cg, int r32, int hi, const float (&ss)[16]) const {
;     ...
;             } else if (pn < 10) {
;                 float q = v0 * v0 + v1 * v1;
;                 q += __shfl_xor(q, 1); q += __shfl_xor(q, 2); q += __shfl_xor(q, 4); q += __shfl_xor(q, 8); q += __shfl_xor(q, 16);
;                 const float rn = rsqrtf(q * (1.0f / 64.0f) + EPS);
;                 const bool isq = pn < 8;
;                 const float* gp = isq ? qg : kg;
;                 const int col = ((pn & 1) * 4 + hd) * 64 + r32;
;                 const float a0 = v0 * rn * gp[r32], a1 = v1 * rn * gp[32 + r32];
;                 if (isq) { bf16_t* SQ = (bf16_t*)(ws + WS_SQ); SQ[(size_t)row * 512 + col] = (bf16_t)f2bf(a0 * QSCALE); SQ[(size_t)row * 512 + col + 32] = (bf16_t)f2bf(a1 * QSCALE); }
;                 else { bf16_t* KB = (bf16_t*)(ws + WS_KB); KB[(size_t)row * 512 + col] = (bf16_t)f2bf(a0); KB[(size_t)row * 512 + col + 32] = (bf16_t)f2bf(a1);
;                     Ks[(size_t)rs_ * 512 + col] = a0; Ks[(size_t)rs_ * 512 + col + 32] = a1; }
.LBB0_476:
	s_andn2_b64 vcc, exec, s[16:17]
	s_cbranch_vccnz .LBB0_481
	s_and_b64 s[16:17], s[44:45], exec
	s_cselect_b32 s17, s62, s64
	s_cselect_b32 s16, s61, s63
	v_lshlrev_b32_e32 v0, 2, v98
	s_nop 0
	v_pk_mul_f32 v[74:75], v[62:63], v[62:63]
	v_xor_b32_e32 v29, 16, v205
	v_add_f32_e32 v23, v74, v75
	ds_bpermute_b32 v27, v69, v23
	v_cmp_lt_i32_e32 vcc, v29, v68
	s_waitcnt lgkmcnt(0)
	v_add_f32_e32 v23, v23, v27
	ds_bpermute_b32 v27, v70, v23
	v_cndmask_b32_e32 v29, v205, v29, vcc
	v_lshlrev_b32_e32 v29, 2, v29
	s_andn2_b64 vcc, exec, s[42:43]
	s_waitcnt lgkmcnt(0)
	v_add_f32_e32 v23, v23, v27
	ds_bpermute_b32 v27, v71, v23
	s_waitcnt lgkmcnt(0)
	v_add_f32_e32 v23, v23, v27
	ds_bpermute_b32 v27, v72, v23
	s_waitcnt lgkmcnt(0)
	v_add_f32_e32 v23, v23, v27
	ds_bpermute_b32 v27, v29, v23
	s_waitcnt lgkmcnt(0)
	v_add_f32_e32 v23, v23, v27
	v_fmamk_f32 v23, v23, 0x3c800000, v201
	v_mul_f32_e32 v27, 0x4b800000, v23
	v_cmp_gt_f32_e64 s[16:17], s3, v23
	s_nop 1
	v_cndmask_b32_e64 v23, v23, v27, s[16:17]
	v_rsq_f32_e32 v23, v23
	s_nop 0
	v_mul_f32_e32 v27, 0x45800000, v23
	v_cndmask_b32_e64 v23, v23, v27, s[16:17]
	v_mul_f32_e32 v27, v62, v23
	v_mul_f32_e32 v23, v63, v23
	s_mov_b64 s[16:17], -1
	v_mul_f32_e32 v21, v198, v27
	v_mul_f32_e32 v0, v199, v23
	s_cbranch_vccnz .LBB0_479
	v_bfe_u32 v23, v21, 16, 1
	v_lshlrev_b64 v[74:75], 10, v[64:65]
	v_add3_u32 v23, v21, v23, s2
	v_lshl_add_u64 v[74:75], v[54:55], 0, v[74:75]
	v_ashrrev_i32_e32 v67, 31, v66
	global_store_short_d16_hi v[74:75], v23, off
	v_bfe_u32 v23, v0, 16, 1
	v_lshlrev_b64 v[66:67], 11, v[66:67]
	v_add3_u32 v23, v0, v23, s2
	v_lshl_add_u64 v[66:67], v[52:53], 0, v[66:67]
	s_mov_b64 s[16:17], 0
	global_store_short_d16_hi v[74:75], v23, off offset:64
	global_store_dword v[66:67], v21, off
	global_store_dword v[66:67], v0, off offset:128

; __device__ __forceinline__ unsigned f2bf(float f) { unsigned u = __builtin_bit_cast(unsigned, f); return (u + 0x7fffu + ((u >> 16) & 1u)) >> 16; }
;     __device__ __forceinline__ void operator()(const f32x16& acc0, const f32x16& acc1, int rb, int cg, int r32, int hi, const float (&ss)[16]) const {
;     ...
;             } else if (pn < 10) {
;                 float q = v0 * v0 + v1 * v1;
;                 q += __shfl_xor(q, 1); q += __shfl_xor(q, 2); q += __shfl_xor(q, 4); q += __shfl_xor(q, 8); q += __shfl_xor(q, 16);
;                 const float rn = rsqrtf(q * (1.0f / 64.0f) + EPS);
;                 const bool isq = pn < 8;
;                 const float* gp = isq ? qg : kg;
;                 const int col = ((pn & 1) * 4 + hd) * 64 + r32;
;                 const float a0 = v0 * rn * gp[r32], a1 = v1 * rn * gp[32 + r32];
;                 if (isq) { bf16_t* SQ = (bf16_t*)(ws + WS_SQ); SQ[(size_t)row * 512 + col] = (bf16_t)f2bf(a0 * QSCALE); SQ[(size_t)row * 512 + col + 32] = (bf16_t)f2bf(a1 * QSCALE); }
;                 else { bf16_t* KB = (bf16_t*)(ws + WS_KB); KB[(size_t)row * 512 + col] = (bf16_t)f2bf(a0); KB[(size_t)row * 512 + col + 32] = (bf16_t)f2bf(a1);
;                     Ks[(size_t)rs_ * 512 + col] = a0; Ks[(size_t)rs_ * 512 + col + 32] = a1; }
.LBB0_524:
	s_andn2_b64 vcc, exec, s[14:15]
	s_cbranch_vccnz .LBB0_529
	s_and_b64 s[12:13], s[44:45], exec
	s_cselect_b32 s13, s62, s64
	s_cselect_b32 s12, s61, s63
	v_lshlrev_b32_e32 v0, 2, v98
	s_nop 0
	v_pk_mul_f32 v[56:57], v[62:63], v[62:63]
	v_xor_b32_e32 v27, 16, v205
	v_add_f32_e32 v23, v56, v57
	ds_bpermute_b32 v25, v69, v23
	v_cmp_lt_i32_e32 vcc, v27, v68
	s_waitcnt lgkmcnt(0)
	v_add_f32_e32 v23, v23, v25
	ds_bpermute_b32 v25, v70, v23
	v_cndmask_b32_e32 v27, v205, v27, vcc
	v_lshlrev_b32_e32 v27, 2, v27
	s_andn2_b64 vcc, exec, s[42:43]
	s_waitcnt lgkmcnt(0)
	v_add_f32_e32 v23, v23, v25
	ds_bpermute_b32 v25, v71, v23
	s_waitcnt lgkmcnt(0)
	v_add_f32_e32 v23, v23, v25
	ds_bpermute_b32 v25, v72, v23
	s_waitcnt lgkmcnt(0)
	v_add_f32_e32 v23, v23, v25
	ds_bpermute_b32 v25, v27, v23
	s_waitcnt lgkmcnt(0)
	v_add_f32_e32 v23, v23, v25
	v_fmamk_f32 v23, v23, 0x3c800000, v201
	v_mul_f32_e32 v25, 0x4b800000, v23
	v_cmp_gt_f32_e64 s[12:13], s3, v23
	s_nop 1
	v_cndmask_b32_e64 v23, v23, v25, s[12:13]
	v_rsq_f32_e32 v23, v23
	s_nop 0
	v_mul_f32_e32 v25, 0x45800000, v23
	v_cndmask_b32_e64 v23, v23, v25, s[12:13]
	v_mul_f32_e32 v25, v62, v23
	v_mul_f32_e32 v23, v63, v23
	s_mov_b64 s[12:13], -1
	v_mul_f32_e32 v21, v198, v25
	v_mul_f32_e32 v0, v199, v23
	s_cbranch_vccnz .LBB0_527
	v_bfe_u32 v23, v21, 16, 1
	v_lshlrev_b64 v[56:57], 10, v[64:65]
	v_add3_u32 v23, v21, v23, s2
	v_lshl_add_u64 v[54:55], v[54:55], 0, v[56:57]
	global_store_short_d16_hi v[54:55], v23, off
	v_bfe_u32 v23, v0, 16, 1
	v_add3_u32 v23, v0, v23, s2
	v_ashrrev_i32_e32 v61, 31, v60
	global_store_short_d16_hi v[54:55], v23, off offset:64
	v_lshlrev_b64 v[54:55], 11, v[60:61]
	v_lshl_add_u64 v[52:53], v[52:53], 0, v[54:55]
	s_mov_b64 s[12:13], 0
	global_store_dword v[52:53], v21, off
	global_store_dword v[52:53], v0, off offset:128
